# vt_tile: 8 row loads of a tile issued together into fresh VGPRs with counted waits (on top of PB grouping version)
# speedup vs baseline: 1.0048x; 1.0048x over previous
; #define LAS __attribute__((address_space(3)))
; DI void vt_tile(const bf16_t* PROJ, bf16_t* VTA, bf16_t* VTB, LAS bf16_t* tl, int tile, int lane) {
;     ...
; #pragma unroll
;     for (int p = 0; p < 8; ++p) { const int tok = 8 * p + (lane >> 3), ch = lane & 7;
;         const u32x4 v = __builtin_nontemporal_load((const u32x4*)(PROJ + (size_t)(row0 + tok) * NINP + col0 + 8 * ch));
;         LAS bf16_t* q = tl + (8 * ch) * 72 + tok;
;         q[0 * 72] = (bf16_t)(v.x & 0xffff); q[1 * 72] = (bf16_t)(v.x >> 16); q[2 * 72] = (bf16_t)(v.y & 0xffff); q[3 * 72] = (bf16_t)(v.y >> 16);
;         q[4 * 72] = (bf16_t)(v.z & 0xffff); q[5 * 72] = (bf16_t)(v.z >> 16); q[6 * 72] = (bf16_t)(v.w & 0xffff); q[7 * 72] = (bf16_t)(v.w >> 16); }
;     asm volatile("s_waitcnt lgkmcnt(0)" ::: "memory");
; #pragma unroll
;     for (int p = 0; p < 8; ++p) { const int c = 8 * p + (lane >> 3), tch = lane & 7;
;         const u32x4 v = *(const LAS u32x4*)(tl + c * 72 + 8 * tch);
;         *(u32x4*)(dst + (size_t)c * SEQ + t0 + 8 * tch) = v; }
;     asm volatile("s_waitcnt lgkmcnt(0)" ::: "memory");
.LBB0_374:
	s_lshl_b32 s3, s15, 6
	v_lshl_add_u64 v[0:1], s[4:5], 1, v[6:7]
	v_add_u32_e32 v2, s3, v4
	v_mad_i64_i32 v[2:3], s[4:5], v2, s90, v[0:1]
	global_load_dwordx4 v[144:147], v[2:3], off nt
	v_add_u32_e32 v2, s3, v8
	v_mad_i64_i32 v[2:3], s[4:5], v2, s90, v[0:1]
	s_bfe_i32 s2, s15, 0x10019
	s_lshr_b32 s2, s2, 21
	s_add_i32 s2, s3, s2
	s_and_b32 s2, s2, 0xfffff800
	s_sub_i32 s2, s3, s2
	v_mov_b32_e32 v39, v98
	global_load_dwordx4 v[148:151], v[2:3], off nt
	v_add_u32_e32 v2, s3, v10
	v_mad_i64_i32 v[2:3], s[4:5], v2, s90, v[0:1]
	global_load_dwordx4 v[152:155], v[2:3], off nt
	v_add_u32_e32 v2, s3, v12
	v_mad_i64_i32 v[2:3], s[4:5], v2, s90, v[0:1]
	global_load_dwordx4 v[156:159], v[2:3], off nt
	v_add_u32_e32 v2, s3, v14
	v_mad_i64_i32 v[2:3], s[4:5], v2, s90, v[0:1]
	global_load_dwordx4 v[160:163], v[2:3], off nt
	v_add_u32_e32 v2, s3, v16
	v_mad_i64_i32 v[2:3], s[4:5], v2, s90, v[0:1]
	global_load_dwordx4 v[164:167], v[2:3], off nt
	v_add_u32_e32 v2, s3, v18
	v_mad_i64_i32 v[2:3], s[4:5], v2, s90, v[0:1]
	global_load_dwordx4 v[168:171], v[2:3], off nt
	v_add_u32_e32 v2, s3, v20
	v_mad_i64_i32 v[0:1], s[4:5], v2, s90, v[0:1]
	s_ashr_i32 s3, s2, 31
	s_lshl_b64 s[2:3], s[2:3], 1
	s_add_u32 s0, s0, s2
	s_addc_u32 s1, s1, s3
	s_add_i32 s8, s8, s70
	s_add_i32 s13, s13, s14
	s_cmpk_gt_i32 s8, 0x11ff
	global_load_dwordx4 v[172:175], v[0:1], off nt
	v_lshl_add_u64 v[42:43], s[0:1], 0, v[38:39]
	v_lshl_add_u64 v[44:45], v[42:43], 0, v[22:23]
	s_waitcnt vmcnt(7)
	ds_write_b16 v40, v144
	ds_write_b16_d16_hi v40, v144 offset:144
	ds_write_b16 v40, v145 offset:288
	ds_write_b16_d16_hi v40, v145 offset:432
	ds_write_b16 v40, v146 offset:576
	ds_write_b16_d16_hi v40, v146 offset:720
	ds_write_b16 v40, v147 offset:864
	ds_write_b16_d16_hi v40, v147 offset:1008
	s_waitcnt vmcnt(6)
	ds_write_b16 v40, v148 offset:16
	ds_write_b16_d16_hi v40, v148 offset:160
	ds_write_b16 v40, v149 offset:304
	ds_write_b16_d16_hi v40, v149 offset:448
	ds_write_b16 v40, v150 offset:592
	ds_write_b16_d16_hi v40, v150 offset:736
	ds_write_b16 v40, v151 offset:880
	ds_write_b16_d16_hi v40, v151 offset:1024
	s_waitcnt vmcnt(5)
	ds_write_b16 v40, v152 offset:32
	ds_write_b16_d16_hi v40, v152 offset:176
	ds_write_b16 v40, v153 offset:320
	ds_write_b16_d16_hi v40, v153 offset:464
	ds_write_b16 v40, v154 offset:608
	ds_write_b16_d16_hi v40, v154 offset:752
	ds_write_b16 v40, v155 offset:896
	ds_write_b16_d16_hi v40, v155 offset:1040
	s_waitcnt vmcnt(4)
	ds_write_b16 v40, v156 offset:48
	ds_write_b16_d16_hi v40, v156 offset:192
	ds_write_b16 v40, v157 offset:336
	ds_write_b16_d16_hi v40, v157 offset:480
	ds_write_b16 v40, v158 offset:624
	ds_write_b16_d16_hi v40, v158 offset:768
	ds_write_b16 v40, v159 offset:912
	ds_write_b16_d16_hi v40, v159 offset:1056
	s_waitcnt vmcnt(3)
	ds_write_b16 v40, v160 offset:64
	ds_write_b16_d16_hi v40, v160 offset:208
	ds_write_b16 v40, v161 offset:352
	ds_write_b16_d16_hi v40, v161 offset:496
	ds_write_b16 v40, v162 offset:640
	ds_write_b16_d16_hi v40, v162 offset:784
	ds_write_b16 v40, v163 offset:928
	ds_write_b16_d16_hi v40, v163 offset:1072
	s_waitcnt vmcnt(2)
	ds_write_b16 v40, v164 offset:80
	ds_write_b16_d16_hi v40, v164 offset:224
	ds_write_b16 v40, v165 offset:368
	ds_write_b16_d16_hi v40, v165 offset:512
	ds_write_b16 v40, v166 offset:656
	ds_write_b16_d16_hi v40, v166 offset:800
	ds_write_b16 v40, v167 offset:944
	ds_write_b16_d16_hi v40, v167 offset:1088
	s_waitcnt vmcnt(1)
	ds_write_b16 v40, v168 offset:96
	ds_write_b16_d16_hi v40, v168 offset:240
	ds_write_b16 v40, v169 offset:384
	ds_write_b16_d16_hi v40, v169 offset:528
	ds_write_b16 v40, v170 offset:672
	ds_write_b16_d16_hi v40, v170 offset:816
	ds_write_b16 v40, v171 offset:960
	ds_write_b16_d16_hi v40, v171 offset:1104
	s_waitcnt vmcnt(0)
	ds_write_b16 v40, v172 offset:112
	ds_write_b16_d16_hi v40, v172 offset:256
	ds_write_b16 v40, v173 offset:400
	ds_write_b16_d16_hi v40, v173 offset:544
	ds_write_b16 v40, v174 offset:688
	ds_write_b16_d16_hi v40, v174 offset:832
	ds_write_b16 v40, v175 offset:976
	ds_write_b16_d16_hi v40, v175 offset:1120
	s_waitcnt lgkmcnt(0)
	ds_read_b128 v[0:3], v5
	s_waitcnt lgkmcnt(0)
	global_store_dwordx4 v[44:45], v[0:3], off
	ds_read_b128 v[0:3], v5 offset:1152
	v_lshl_add_u64 v[44:45], v[42:43], 0, v[24:25]
	s_waitcnt lgkmcnt(0)
	global_store_dwordx4 v[44:45], v[0:3], off
	ds_read_b128 v[0:3], v5 offset:2304
	v_lshl_add_u64 v[44:45], v[42:43], 0, v[26:27]
	s_waitcnt lgkmcnt(0)
	global_store_dwordx4 v[44:45], v[0:3], off
	ds_read_b128 v[0:3], v5 offset:3456
	v_lshl_add_u64 v[44:45], v[42:43], 0, v[28:29]
	s_waitcnt lgkmcnt(0)
	global_store_dwordx4 v[44:45], v[0:3], off
	ds_read_b128 v[0:3], v5 offset:4608
	v_lshl_add_u64 v[44:45], v[42:43], 0, v[30:31]
	s_waitcnt lgkmcnt(0)
	global_store_dwordx4 v[44:45], v[0:3], off
	ds_read_b128 v[0:3], v5 offset:5760
	v_lshl_add_u64 v[44:45], v[42:43], 0, v[32:33]
	s_waitcnt lgkmcnt(0)
	global_store_dwordx4 v[44:45], v[0:3], off
	ds_read_b128 v[0:3], v5 offset:6912
	v_lshl_add_u64 v[44:45], v[42:43], 0, v[34:35]
	v_lshl_add_u64 v[42:43], v[42:43], 0, v[36:37]
	s_waitcnt lgkmcnt(0)
	global_store_dwordx4 v[44:45], v[0:3], off
	ds_read_b128 v[0:3], v5 offset:8064
	s_waitcnt lgkmcnt(0)
	global_store_dwordx4 v[42:43], v[0:3], off
	s_waitcnt lgkmcnt(0)
	s_cbranch_scc1 .LBB0_379
